# stack: G1B sigmoid rcp+Newton, G5 third round as half-M tiles, m2 second pass moved to blocks 254/255, accumulator zeroing hoisted, p2 silu division chains via rcp+Newton
# speedup vs baseline: 1.0071x; 1.0070x over previous
; #define WAIT_V(n) asm volatile("s_waitcnt vmcnt(" #n ")" ::: "memory")
; #define BAR __builtin_amdgcn_s_barrier()
; DEVI void gemm256(const P& p, const u16* A, int lda, const u16* Bt, int ldb, int K, int brow, int bcol, int mode,
;                         int aux, int layer, int bmode) {
;     ...
;   int wid = TIDX >> 6, lane = TIDX & 63, wr = wid >> 2, wc = wid & 3, fr = lane & 15, fq = lane >> 4;
;     ...
;   f32x4 acc[2][2][4][2] = {};
;   bf16x8 At[4][2], B0[2][2], B1[2][2];
;     ...
;   f32x4 acc[2][1][4][2] = {};
;   bf16x8 At[4][2], B0[2][2];
;     ...
;   int nt = K / BK;
;   const int bhalf = bmode ? 4096 : HALF;
;   int offA0, offA1, offB0, offB1;
;   __amdgpu_buffer_rsrc_t rsA = __builtin_amdgcn_make_buffer_rsrc((void*)A, 0, 0x7fffffff, 0x00020000);
;   __amdgpu_buffer_rsrc_t rsB = __builtin_amdgcn_make_buffer_rsrc((void*)Bt, 0, 0x7fffffff, 0x00020000);
;   {
;     int r0, c0, r1, c1;
;     stage_rc(TIDX * 16, r0, c0);
;     stage_rc(TIDX * 16 + 8192, r1, c1);
;     offA0 = (r0 * lda + c0) * 2; offA1 = (r1 * lda + c1) * 2;
;     offB0 = (r0 * ldb + c0) * 2; offB1 = bmode ? offB0 + 2048 * ldb * 2 : (r1 * ldb + c1) * 2;
;   }
;     ...
;   STAGEB(SB(0, 0), bcol, 0);
;   STAGEA(SA(0, 0), brow, 0);
;   STAGEB(SB(0, 1), bcol + bhalf, 0);
;   STAGEA(SA(0, 1), brow + HALF, 0);
;   if (wr == 1) BAR;
;   WAIT_V(4);
;   BAR;
;   STAGEB(SB(1, 0), bcol, 1);
;   STAGEA(SA(1, 0), brow, 1);
;   STAGEB(SB(1, 1), bcol + bhalf, 1);
;   WAIT_V(6);
;   BAR;
.LBB0_189:
	s_lshl_b32 s70, s4, 8
	s_cmp_eq_u32 s98, 2
	s_cselect_b32 s99, 0x80, 0
	s_add_i32 s70, s70, s99
	s_mul_i32 s97, s7, s6
	s_and_b64 s[2:3], s[46:47], exec
	s_movk_i32 s2, 0x80
	s_mul_i32 s3, s97, s5
	s_cselect_b32 s2, s2, 0x1000
	s_lshl_b32 s6, s3, 1
	v_readlane_b32 s3, v249, 20
	s_add_i32 s2, s97, s2
	s_and_b32 s29, s29, 0xffff
	v_add_u32_e32 v145, s3, v0
	v_add_u32_e32 v146, 0x2000, v145
	v_readfirstlane_b32 s3, v145
	s_mov_b32 m0, s3
	v_readfirstlane_b32 s3, v146
	v_add_u32_e32 v147, 16, v0
	s_mul_i32 s2, s2, s5
	v_mul_lo_u32 v2, v2, s9
	buffer_load_dwordx4 v136, s[28:31], s6 offen lds
	s_mov_b32 m0, s3
	s_mul_i32 s7, s9, s70
	v_readfirstlane_b32 s3, v147
	v_add_u32_e32 v148, 0x2000, v147
	s_lshl_b32 s8, s2, 1
	v_readlane_b32 s2, v249, 21
	s_and_b32 s45, s45, 0xffff
	s_mov_b32 s46, s30
	s_mov_b32 s47, s31
	v_add_lshl_u32 v143, v3, v2, 1
	v_mul_lo_u32 v2, v4, s9
	buffer_load_dwordx4 v137, s[28:31], s6 offen lds
	s_lshl_b32 s10, s7, 1
	s_mov_b32 m0, s3
	v_readfirstlane_b32 s3, v148
	v_add_u32_e32 v150, s2, v0
	v_add_lshl_u32 v142, v5, v2, 1
	buffer_load_dwordx4 v143, s[44:47], s10 offen lds
	s_mov_b32 m0, s3
	v_readfirstlane_b32 s2, v150
	v_add_u32_e32 v151, 0x2000, v150
	buffer_load_dwordx4 v142, s[44:47], s10 offen lds
	s_mov_b32 m0, s2
	v_readfirstlane_b32 s2, v151
	buffer_load_dwordx4 v136, s[28:31], s8 offen lds
	s_mov_b32 m0, s2
	s_lshl_b32 s2, s9, 7
	v_add_u32_e32 v152, 0x4000, v147
	s_add_i32 s7, s7, s2
	v_readfirstlane_b32 s3, v152
	v_add_u32_e32 v153, 0x6000, v147
	buffer_load_dwordx4 v137, s[28:31], s8 offen lds
	s_lshl_b32 s2, s7, 1
	s_mov_b32 m0, s3
	v_readfirstlane_b32 s3, v153
	buffer_load_dwordx4 v143, s[44:47], s2 offen lds
	s_mov_b32 m0, s3
	v_ashrrev_i32_e32 v132, 8, v130
	buffer_load_dwordx4 v142, s[44:47], s2 offen lds
	v_mov_b32_e32 v62, 0
	v_mov_b32_e32 v63, 0
	v_mov_b32_e32 v64, 0
	v_mov_b32_e32 v65, 0
	v_mov_b32_e32 v82, 0
	v_mov_b32_e32 v83, 0
	v_mov_b32_e32 v84, 0
	v_mov_b32_e32 v85, 0
	v_mov_b32_e32 v98, 0
	v_mov_b32_e32 v99, 0
	v_mov_b32_e32 v100, 0
	v_mov_b32_e32 v101, 0
	v_mov_b32_e32 v110, 0
	v_mov_b32_e32 v111, 0
	v_mov_b32_e32 v112, 0
	v_mov_b32_e32 v113, 0
	v_mov_b32_e32 v114, 0
	v_mov_b32_e32 v115, 0
	v_mov_b32_e32 v116, 0
	v_mov_b32_e32 v117, 0
	v_mov_b32_e32 v118, 0
	v_mov_b32_e32 v119, 0
	v_mov_b32_e32 v120, 0
	v_mov_b32_e32 v121, 0
	v_mov_b32_e32 v122, 0
	v_mov_b32_e32 v123, 0
	v_mov_b32_e32 v124, 0
	v_mov_b32_e32 v125, 0
	v_mov_b32_e32 v126, 0
	v_mov_b32_e32 v127, 0
	v_mov_b32_e32 v128, 0
	v_mov_b32_e32 v129, 0
	v_mov_b32_e32 v34, 0
	v_mov_b32_e32 v35, 0
	v_mov_b32_e32 v36, 0
	v_mov_b32_e32 v37, 0
	v_mov_b32_e32 v38, 0
	v_mov_b32_e32 v39, 0
	v_mov_b32_e32 v40, 0
	v_mov_b32_e32 v41, 0
	v_mov_b32_e32 v42, 0
	v_mov_b32_e32 v43, 0
	v_mov_b32_e32 v44, 0
	v_mov_b32_e32 v45, 0
	v_mov_b32_e32 v46, 0
	v_mov_b32_e32 v47, 0
	v_mov_b32_e32 v48, 0
	v_mov_b32_e32 v49, 0
	v_mov_b32_e32 v50, 0
	v_mov_b32_e32 v51, 0
	v_mov_b32_e32 v52, 0
	v_mov_b32_e32 v53, 0
	v_mov_b32_e32 v54, 0
	v_mov_b32_e32 v55, 0
	v_mov_b32_e32 v56, 0
	v_mov_b32_e32 v57, 0
	v_mov_b32_e32 v58, 0
	v_mov_b32_e32 v59, 0
	v_mov_b32_e32 v60, 0
	v_mov_b32_e32 v61, 0
	v_mov_b32_e32 v70, 0
	v_mov_b32_e32 v71, 0
	v_mov_b32_e32 v72, 0
	v_mov_b32_e32 v73, 0
	v_mov_b32_e32 v66, 0
	v_mov_b32_e32 v67, 0
	v_mov_b32_e32 v68, 0
	v_mov_b32_e32 v69, 0
	v_mov_b32_e32 v74, 0
	v_mov_b32_e32 v75, 0
	v_mov_b32_e32 v76, 0
	v_mov_b32_e32 v77, 0
	v_mov_b32_e32 v78, 0
	v_mov_b32_e32 v79, 0
	v_mov_b32_e32 v80, 0
	v_mov_b32_e32 v81, 0
	v_mov_b32_e32 v86, 0
	v_mov_b32_e32 v87, 0
	v_mov_b32_e32 v88, 0
	v_mov_b32_e32 v89, 0
	v_mov_b32_e32 v90, 0
	v_mov_b32_e32 v91, 0
	v_mov_b32_e32 v92, 0
	v_mov_b32_e32 v93, 0
	v_mov_b32_e32 v94, 0
	v_mov_b32_e32 v95, 0
	v_mov_b32_e32 v96, 0
	v_mov_b32_e32 v97, 0
	v_mov_b32_e32 v102, 0
	v_mov_b32_e32 v103, 0
	v_mov_b32_e32 v104, 0
	v_mov_b32_e32 v105, 0
	v_mov_b32_e32 v106, 0
	v_mov_b32_e32 v107, 0
	v_mov_b32_e32 v108, 0
	v_mov_b32_e32 v109, 0
	v_cmp_eq_u32_e32 vcc, 1, v132
	s_and_saveexec_b64 s[2:3], vcc
	s_cbranch_execz .LBB0_191
	s_barrier
; #define WAIT_V(n) asm volatile("s_waitcnt vmcnt(" #n ")" ::: "memory")
; #define BAR __builtin_amdgcn_s_barrier()
; DEVI void gemm256(const P& p, const u16* A, int lda, const u16* Bt, int ldb, int K, int brow, int bcol, int mode,
;                         int aux, int layer, int bmode) {
;     ...
;   {
;     int r0, c0, r1, c1;
;     stage_rc(TIDX * 16, r0, c0);
;     stage_rc(TIDX * 16 + 8192, r1, c1);
;     offA0 = (r0 * lda + c0) * 2; offA1 = (r1 * lda + c1) * 2;
;     offB0 = (r0 * ldb + c0) * 2; offB1 = bmode ? offB0 + 2048 * ldb * 2 : (r1 * ldb + c1) * 2;
;   }
;     ...
;   STAGEB(SB(0, 0), bcol, 0);
;   STAGEA(SA(0, 0), brow, 0);
;   STAGEB(SB(0, 1), bcol + bhalf, 0);
;   STAGEA(SA(0, 1), brow + HALF, 0);
;   if (wr == 1) BAR;
;   WAIT_V(4);
;   BAR;
;   STAGEB(SB(1, 0), bcol, 1);
;   STAGEA(SA(1, 0), brow, 1);
;   STAGEB(SB(1, 1), bcol + bhalf, 1);
;   WAIT_V(6);
;   BAR;
.LBB0_191:
	s_or_b64 exec, exec, s[2:3]
	v_readlane_b32 s12, v249, 22
	s_or_b32 s3, s6, 0x80
	s_waitcnt vmcnt(4)
	s_barrier
	v_add_u32_e32 v154, s12, v0
	v_add_u32_e32 v155, 0x2000, v154
	v_readfirstlane_b32 s11, v154
	s_mov_b32 m0, s11
	v_readfirstlane_b32 s11, v155
	buffer_load_dwordx4 v136, s[28:31], s3 offen lds
	s_mov_b32 m0, s11
	v_add_u32_e32 v156, 0x8000, v147
	buffer_load_dwordx4 v137, s[28:31], s3 offen lds
	v_readfirstlane_b32 s3, v156
	v_add_u32_e32 v157, 0xa000, v147
	s_bitset1_b32 s10, 7
	s_mov_b32 s46, s30
	s_mov_b32 s47, s31
	s_mov_b32 m0, s3
	v_readfirstlane_b32 s3, v157
	v_readlane_b32 s11, v249, 23
	buffer_load_dwordx4 v143, s[44:47], s10 offen lds
	s_mov_b32 m0, s3
	v_add_u32_e32 v161, s11, v0
	buffer_load_dwordx4 v142, s[44:47], s10 offen lds
	v_readfirstlane_b32 s10, v161
	v_add_u32_e32 v162, 0x2000, v161
	s_or_b32 s3, s8, 0x80
	s_mov_b32 m0, s10
	v_readfirstlane_b32 s10, v162
	buffer_load_dwordx4 v136, s[28:31], s3 offen lds
	s_mov_b32 m0, s10
	v_and_b32_e32 v131, 15, v130
	buffer_load_dwordx4 v137, s[28:31], s3 offen lds
	v_bfe_u32 v134, v130, 4, 2
	v_lshlrev_b32_e32 v4, 2, v130
	v_lshlrev_b32_e32 v2, 4, v134
	v_lshlrev_b32_e32 v3, 6, v131
	v_and_b32_e32 v4, 32, v4
	v_bitop3_b32 v3, v2, v4, v3 bitop3:0x36
	v_readlane_b32 s3, v249, 20
	v_lshrrev_b32_e32 v133, 4, v130
	s_waitcnt vmcnt(27)
	v_lshlrev_b32_e32 v11, 6, v130
	v_add_u32_e32 v5, s3, v3
	v_readlane_b32 s3, v249, 21
	s_waitcnt vmcnt(6)
	v_and_b32_e32 v135, 12, v133
	v_lshlrev_b32_e32 v10, 13, v132
	v_add_u32_e32 v6, s3, v3
	s_movk_i32 s3, 0x3c0
	v_and_or_b32 v2, v11, s3, v2
	s_add_i32 s3, s70, 0x80
	s_lshr_b32 s2, s5, 6
	v_add_u32_e32 v7, s12, v3
	v_add_u32_e32 v8, s11, v3
	v_lshlrev_b32_e32 v9, 10, v135
	v_add_u32_e32 v3, 16, v3
	v_xad_u32 v4, v2, v4, 16
	v_or_b32_e32 v11, 0x800, v10
	v_or_b32_e32 v12, 0x1000, v10
	v_or_b32_e32 v13, 0x1800, v10
	s_mul_i32 s3, s9, s3
	s_lshl_b32 s4, s4, 9
	v_mov_b32_e32 v2, 0
	s_xor_b64 s[36:37], s[36:37], -1
	s_xor_b64 s[78:79], s[54:55], -1
	s_add_i32 s2, s2, -2
	v_add_u32_e32 v159, 0xc000, v147
	v_add_u32_e32 v158, 0xe000, v147
	s_lshl_b32 s3, s3, 1
	s_mul_i32 s9, s4, s9
	s_cmp_eq_u32 s98, 2
	s_cselect_b32 s99, 0x80000, 0
	s_add_i32 s9, s9, s99
	s_mov_b32 s10, 0
	v_add_u32_e32 v163, v5, v9
	v_add_u32_e32 v141, v3, v10
	v_add_u32_e32 v140, v4, v11
	v_add_u32_e32 v139, v4, v12
	v_add_u32_e32 v138, v4, v13
	v_add_u32_e32 v160, v6, v9
	v_add_u32_e32 v149, v7, v9
	v_add_u32_e32 v144, v8, v9
	s_mov_b32 s11, 0
	v_mov_b32_e32 v3, v2
	v_mov_b32_e32 v4, v2
	v_mov_b32_e32 v5, v2
	v_mov_b32_e32 v6, v2
	v_mov_b32_e32 v7, v2
	v_mov_b32_e32 v8, v2
	v_mov_b32_e32 v9, v2
	v_mov_b32_e32 v10, v2
	v_mov_b32_e32 v11, v2
	v_mov_b32_e32 v12, v2
	v_mov_b32_e32 v13, v2
	s_waitcnt vmcnt(26)
	v_mov_b32_e32 v14, v2
	v_mov_b32_e32 v15, v2
	v_mov_b32_e32 v16, v2
	v_mov_b32_e32 v17, v2
	s_waitcnt vmcnt(25)
	v_mov_b32_e32 v18, v2
	v_mov_b32_e32 v19, v2
	v_mov_b32_e32 v20, v2
	v_mov_b32_e32 v21, v2
	s_waitcnt vmcnt(24)
	v_mov_b32_e32 v22, v2
	v_mov_b32_e32 v23, v2
	v_mov_b32_e32 v24, v2
	v_mov_b32_e32 v25, v2
	s_waitcnt vmcnt(23)
	v_mov_b32_e32 v26, v2
	v_mov_b32_e32 v27, v2
	v_mov_b32_e32 v28, v2
	v_mov_b32_e32 v29, v2
	s_waitcnt vmcnt(22)
	v_mov_b32_e32 v30, v2
	v_mov_b32_e32 v31, v2
	v_mov_b32_e32 v32, v2
	v_mov_b32_e32 v33, v2
	s_waitcnt vmcnt(14)
	s_barrier
	s_cmp_lg_u32 s98, 0
	s_cbranch_scc1 .Lhm_192

; #define opqp(x) ((x) + opqz())
; __device__ void phase_m2(const P& p) {
;   OPQ_IDS
;   char* ws = opqp(p.ws);
;   const float* kloc = (const float*)(ws + O_KLOC);
;   const float* nloc = (const float*)(ws + O_NLOC);
;   const float* sc = (const float*)(ws + O_SC);
;   u16* cin = (u16*)(ws + O_CIN);
;   float* nin = (float*)(ws + O_NIN);
;   float* minp = (float*)(ws + O_MIN);
;   const int per = 4096 + 32;
;   for (int idx = BIDX * NTHR + TIDX; idx < 32 * per; idx += gridDim.x * NTHR) {
;     int seq = idx / per, q4 = idx % per;
;     f32x4 C = {0.f, 0.f, 0.f, 0.f};
;     float m = 0.f;
;     const bool isn = q4 >= 4096;
;     f32x4 kvA[4], kvB[4];
;     float blA[4], mlA[4], blB[4], mlB[4];
.LBB0_506:
	s_andn2_b64 vcc, exec, s[0:1]
	s_cbranch_vccnz .LBB0_802
	v_readlane_b32 s0, v249, 56
	s_and_b32 s0, 0xffff, s0
	s_cmp_lg_u32 s0, 4
	s_cbranch_scc1 .LBB0_802
	v_mov_b32_e32 v0, v171
	s_mov_b32 s2, s26
	s_mov_b64 s[0:1], 0
	v_lshl_add_u32 v88, s2, 9, v0
	s_mov_b32 s2, 0x20400
	v_cmp_gt_i32_e32 vcc, s2, v88
	s_and_saveexec_b64 s[28:29], vcc
	s_cbranch_execz .LBB0_634
	s_add_u32 s0, s72, s0
	s_addc_u32 s1, s73, s1
	s_add_u32 s34, s0, 0x2aa3c000
	s_addc_u32 s35, s1, 0
	s_add_u32 s36, s0, 0x3323c000
	s_addc_u32 s37, s1, 0
	s_add_u32 s40, s0, 0x3334c000
	s_addc_u32 s41, s1, 0
	s_add_u32 s42, s0, 0x33350400
	s_addc_u32 s43, s1, 0
	s_add_u32 s44, s0, 0x37750400
	s_addc_u32 s45, s1, 0
	s_add_u32 s46, s0, 0x37860400
	s_addc_u32 s47, s1, 0
	s_mov_b64 s[48:49], 0
	s_mov_b32 s99, 0x40000
	s_cmp_ge_u32 s26, 254
	s_cselect_b32 s99, 0x400, s99
	s_branch .LBB0_512

; __device__ void phase_m2(const P& p) {
;     ...
;   for (int idx = BIDX * NTHR + TIDX; idx < 32 * per; idx += gridDim.x * NTHR) {
.LBB0_511:
	s_or_b64 exec, exec, s[0:1]
	v_add_u32_e32 v88, s99, v88
	s_mov_b32 s0, 0x203ff
	v_cmp_lt_i32_e32 vcc, s0, v88
	s_or_b64 s[48:49], vcc, s[48:49]
	s_andn2_b64 exec, exec, s[48:49]
	s_cbranch_execz .LBB0_634
